# HGRN2 scan role rebalancing: waves 4-7 compute the next tile's gate math of their partner recurrence wave (rows loaded by themselves) and hand 38 values over through LDS across barrier A; waves 0-3 sk
# baseline (speedup 1.0000x reference)
; __device__ __forceinline__ float sigmoid_(float x) { return __builtin_amdgcn_rcpf(1.f + __expf(-x)); }
; __device__ __forceinline__ int tid_() { int t = threadIdx.x; asm volatile("" : "+v"(t)); return t; }
; __device__ __forceinline__ int scan_row(int b, int d, int i) {
;     if (i < TC) { const int t = d ? (TC - 1 - i) : i; return MLAT + b * TC + t; }
;     int t = i - TC; if (d) t = TL - 1 - t; return b * TL + t;
; }
; __device__ __forceinline__ void scan_hgrn_mfma(const Params& P, unsigned char* LB, int l, int c) {
;     using CL = ChunkLds<128, 64>;
;     const int tid = tid_(), lane = tid & 63, wave = __builtin_amdgcn_readfirstlane(tid >> 6), fr = lane & 15, fq = lane >> 4;
;     const int vq = c & 1, b = c >> 4, h = (c >> 2) & 3, d = (c >> 1) & 1;
;     const float* U = (const float*)(P.ws + WS_U); bf16* YD = (bf16*)(P.ws + WS_YD);
;     unsigned char* OP = LB;
;     float* tot = (float*)(LB + 58368);
;     const int k = 2 * lane, qt = wave & 3, cb = wave >> 2;
;     const int vv_ = tid & 63, vqt = wave & 3, vc = wave >> 2;
;     f32x2 lb2 = {0.f, 0.f};
;     if (l == 1) { const f32x2 g0 = *(const f32x2*)(P.hgrn_lb_logits + (size_t)(d * 2 + 0) * 512 + h * 128 + k), g1 = *(const f32x2*)(P.hgrn_lb_logits + (size_t)(d * 2 + 1) * 512 + h * 128 + k);
;         lb2.x = sigmoid_(g1.x - g0.x); lb2.y = sigmoid_(g1.y - g0.y); }
;     __syncthreads();
;     zero_operand_pads<128, 64>(OP, tid, 512);
;     f32x4 S[8];
; #pragma unroll
;     for (int i = 0; i < 8; ++i) S[i] = (f32x4){0.f, 0.f, 0.f, 0.f};
;     f32x2 pq[4], pf[4]; float pv[4] = {0.f, 0.f, 0.f, 0.f};
;     ...
;     HGM_LOAD(0);
.LBB0_159:
	s_or_b64 exec, exec, s[6:7]
	s_ashr_i32 s12, s11, 6
	s_and_b32 s21, s12, 3
	s_ashr_i32 s13, s11, 8
	s_ashr_i32 s6, s89, 4
	s_lshl_b32 s7, s13, 4
	s_lshl_b32 s8, s21, 2
	s_or_b32 s38, s8, s7
	s_lshl_b32 s39, s6, 8
	s_lshl_b32 s36, s6, 11
	s_addk_i32 s39, 0x2000
	s_or_b32 s8, s38, 2
	s_add_i32 s6, s38, 0xffffff02
	s_cmpk_lt_i32 s8, 0x100
	s_cselect_b32 s9, 0xff, s33
	s_cselect_b32 s11, s8, s6
	s_cselect_b32 s14, s39, s36
	s_or_b32 s6, s38, 3
	s_add_i32 s7, s38, 0xffffff03
	s_cmpk_lt_i32 s6, 0x100
	s_cselect_b32 s15, 0xff, s33
	s_cselect_b32 s16, s6, s7
	s_cselect_b32 s17, s39, s36
	s_sub_i32 s15, s15, s6
	s_cmp_eq_u32 s20, 0
	s_cselect_b64 s[6:7], -1, 0
	s_and_b64 s[6:7], s[6:7], exec
	s_cselect_b32 s16, s16, s15
	s_sub_i32 s8, s9, s8
	s_cmp_eq_u32 s20, 0
	s_cselect_b64 s[6:7], -1, 0
	s_and_b64 s[6:7], s[6:7], exec
	s_cselect_b32 s15, s11, s8
	s_or_b32 s6, s38, 1
	s_add_i32 s7, s38, 0xffffff01
	s_cmpk_lt_i32 s6, 0x100
	s_cselect_b32 s8, 0xff, s33
	s_cselect_b32 s9, s6, s7
	s_cselect_b32 s11, s39, s36
	s_sub_i32 s8, s8, s6
	s_cmp_eq_u32 s20, 0
	s_cselect_b64 s[6:7], -1, 0
	s_and_b64 s[6:7], s[6:7], exec
	s_cselect_b32 s18, s9, s8
	s_add_i32 s6, s38, 0xffffff00
	s_cmpk_lt_i32 s38, 0x100
	s_cselect_b32 s7, 0xff, s33
	s_cselect_b32 s19, s38, s6
	s_cselect_b32 s23, s39, s36
	s_sub_i32 s22, s7, s38
	s_cmp_eq_u32 s20, 0
	s_cselect_b64 s[6:7], -1, 0
	s_and_b64 s[8:9], s[6:7], exec
	s_cselect_b32 s8, s19, s22
	s_add_i32 s26, s8, s23
	s_lshl_b32 s22, s10, 7
	s_mul_i32 s9, s26, 0x1400
	v_readlane_b32 s42, v255, 35
	s_mul_hi_i32 s8, s26, 0x1400
	v_readlane_b32 s43, v255, 36
	s_add_u32 s24, s42, s9
	s_mul_i32 s23, s26, 0x2a00
	s_addc_u32 s27, s43, s8
	s_mul_hi_i32 s19, s26, 0x2a00
	s_add_u32 s8, s94, s23
	s_addc_u32 s9, s95, s19
	s_lshl_b32 s25, s10, 8
	s_add_u32 s8, s8, s25
	s_addc_u32 s9, s9, 0
	v_lshlrev_b32_e32 v8, 1, v2
	v_mov_b32_e32 v9, v3
	s_lshl_b32 s23, s20, 11
	v_lshl_add_u64 v[10:11], s[8:9], 0, v[8:9]
	s_add_u32 s8, s24, s23
	s_addc_u32 s9, s27, 0
	s_lshl_b32 s24, s10, 9
	s_add_u32 s8, s8, s24
	s_addc_u32 s9, s9, 0
	s_add_i32 s27, s18, s11
	s_mul_i32 s11, s27, 0x1400
	s_mul_hi_i32 s10, s27, 0x1400
	s_add_u32 s28, s42, s11
	s_mul_i32 s19, s27, 0x2a00
	s_addc_u32 s29, s43, s10
	s_mul_hi_i32 s18, s27, 0x2a00
	s_add_u32 s10, s94, s19
	s_addc_u32 s11, s95, s18
	s_add_u32 s10, s10, s25
	s_addc_u32 s11, s11, 0
	v_lshl_add_u64 v[12:13], s[10:11], 0, v[8:9]
	s_add_u32 s10, s28, s23
	s_addc_u32 s11, s29, 0
	s_add_u32 s10, s10, s24
	s_addc_u32 s11, s11, 0
	s_add_i32 s28, s15, s14
	s_mul_i32 s15, s28, 0x1400
	s_mul_hi_i32 s14, s28, 0x1400
	s_add_u32 s29, s42, s15
	s_mul_i32 s19, s28, 0x2a00
	s_addc_u32 s30, s43, s14
	s_mul_hi_i32 s18, s28, 0x2a00
	s_add_u32 s14, s94, s19
	s_addc_u32 s15, s95, s18
	s_add_u32 s14, s14, s25
	s_addc_u32 s15, s15, 0
	v_lshl_add_u64 v[14:15], s[14:15], 0, v[8:9]
	s_add_u32 s14, s29, s23
	s_addc_u32 s15, s30, 0
	s_add_u32 s14, s14, s24
	s_addc_u32 s15, s15, 0
	s_add_i32 s29, s16, s17
	s_mul_i32 s17, s29, 0x1400
	s_mul_hi_i32 s16, s29, 0x1400
	s_add_u32 s18, s42, s17
	s_addc_u32 s19, s43, s16
	s_mul_i32 s17, s29, 0x2a00
	s_mov_b32 s2, 0x26201000
	s_mul_hi_i32 s16, s29, 0x2a00
	s_add_u32 s17, s94, s17
	v_add_co_u32_e32 v10, vcc, s2, v10
	s_addc_u32 s30, s95, s16
	s_nop 0
	v_addc_co_u32_e32 v11, vcc, 0, v11, vcc
	s_add_u32 s16, s17, s25
	v_add_co_u32_e32 v12, vcc, s2, v12
	s_addc_u32 s17, s30, 0
	s_nop 0
	v_addc_co_u32_e32 v13, vcc, 0, v13, vcc
	v_lshl_add_u64 v[8:9], s[16:17], 0, v[8:9]
	s_add_u32 s16, s18, s23
	v_add_co_u32_e32 v14, vcc, s2, v14
	s_addc_u32 s17, s19, 0
	s_nop 0
	v_addc_co_u32_e32 v15, vcc, 0, v15, vcc
	s_add_u32 s16, s16, s24
	v_add_co_u32_e32 v8, vcc, s2, v8
	s_addc_u32 s17, s17, 0
	v_readlane_b32 s2, v255, 45
	s_add_u32 s18, s2, s25
	v_readlane_b32 s2, v255, 46
	s_addc_u32 s19, s2, 0
	s_lshl_b32 s30, s89, 7
	s_and_b32 s31, s30, 0x80
	s_add_u32 s18, s18, s31
	s_addc_u32 s19, s19, 0
	v_addc_co_u32_e32 v9, vcc, 0, v9, vcc
	v_lshl_add_u64 v[56:57], s[18:19], 0, v[2:3]
	global_load_dword v5, v[10:11], off offset:2048
	global_load_dword v16, v[12:13], off offset:2048
	s_nop 0
	global_load_dword v14, v[14:15], off offset:2048
	s_nop 0
	global_load_dword v15, v[8:9], off offset:2048
	v_mad_i64_i32 v[8:9], s[18:19], s26, v190, v[56:57]
	v_mad_i64_i32 v[10:11], s[18:19], s27, v190, v[56:57]
	v_mad_i64_i32 v[12:13], s[18:19], s29, v190, v[56:57]
	global_load_ushort v12, v[12:13], off
	s_nop 0
	global_load_ushort v13, v[8:9], off
	s_nop 0
	global_load_ushort v10, v[10:11], off
	v_mad_i64_i32 v[8:9], s[18:19], s28, v190, v[56:57]
	global_load_ushort v8, v[8:9], off
	s_nop 0
	global_load_dwordx2 v[66:67], v4, s[8:9] offset:64
	global_load_dwordx2 v[64:65], v4, s[10:11] offset:64
	global_load_dwordx2 v[62:63], v4, s[14:15] offset:64
	global_load_dwordx2 v[58:59], v4, s[16:17] offset:64
	s_lshl_b32 s8, s13, 11
	s_add_i32 s8, s8, 0
	s_lshl_b32 s9, s21, 9
	s_mulk_i32 s13, 0x7100
	s_add_i32 s9, s8, s9
	s_add_i32 s37, s13, 0
	s_cmp_lt_u32 s21, 2
	s_cselect_b64 s[26:27], -1, 0
	s_cmp_eq_u32 s21, 0
	s_cselect_b64 s[18:19], -1, 0
	s_cmp_eq_u32 s21, 3
	v_lshrrev_b32_e32 v9, 4, v7
	s_cselect_b64 s[16:17], -1, 0
	s_movk_i32 s2, 0xa0
	s_lshl_b32 s34, s21, 3
	v_and_b32_e32 v116, 15, v6
	s_cmp_lt_i32 s12, 4
	s_waitcnt vmcnt(0)
; __device__ __forceinline__ float sigmoid_(float x) { return __builtin_amdgcn_rcpf(1.f + __expf(-x)); }
; __device__ __forceinline__ void scan_hgrn_mfma(const Params& P, unsigned char* LB, int l, int c) {
;     ...
;     const int k = 2 * lane, qt = wave & 3, cb = wave >> 2;
;     const int vv_ = tid & 63, vqt = wave & 3, vc = wave >> 2;
;     f32x2 lb2 = {0.f, 0.f};
;     if (l == 1) { const f32x2 g0 = *(const f32x2*)(P.hgrn_lb_logits + (size_t)(d * 2 + 0) * 512 + h * 128 + k), g1 = *(const f32x2*)(P.hgrn_lb_logits + (size_t)(d * 2 + 1) * 512 + h * 128 + k);
;         lb2.x = sigmoid_(g1.x - g0.x); lb2.y = sigmoid_(g1.y - g0.y); }
;     __syncthreads();
;     zero_operand_pads<128, 64>(OP, tid, 512);
;     f32x4 S[8];
; #pragma unroll
;     for (int i = 0; i < 8; ++i) S[i] = (f32x4){0.f, 0.f, 0.f, 0.f};
;     f32x2 pq[4], pf[4]; float pv[4] = {0.f, 0.f, 0.f, 0.f};
;     ...
;     HGM_LOAD(0);
	v_and_b32_e32 v119, 48, v6
	v_lshlrev_b32_e32 v6, 2, v9
	v_add_u32_e32 v125, s9, v4
	v_add_u32_e32 v124, s8, v4
	s_cselect_b64 s[28:29], -1, 0
	v_lshlrev_b32_e32 v121, 3, v7
	s_lshl_b32 s30, s12, 4
	v_cmp_gt_u32_e64 s[14:15], v6, v116
	v_cmp_lt_u32_e64 s[8:9], v6, v116
	s_mulk_i32 s20, 0x2400
	s_add_i32 s58, s20, 0x9000
	v_lshlrev_b32_e32 v52, 3, v9
	v_mov_b32_e32 v53, v3
	v_mov_b32_e32 v32, 0
	s_mov_b32 s40, 0
	v_pk_add_f32 v[54:55], v[0:1], 1.0 op_sel_hi:[1,0] neg_lo:[1,0] neg_hi:[1,0]
	v_mul_u32_u24_e32 v118, 0x50, v116
	v_add_u32_e32 v117, 0, v119
	v_sub_u32_e32 v126, 0, v116
	v_lshlrev_b32_e32 v2, 1, v2
	s_mov_b32 s44, 0
	v_mov_b32_e32 v33, v32
	v_mov_b32_e32 v34, v32
	v_mov_b32_e32 v35, v32
	v_mov_b32_e32 v28, v32
	v_mov_b32_e32 v29, v32
	v_mov_b32_e32 v30, v32
	v_mov_b32_e32 v31, v32
	v_mov_b32_e32 v24, v32
	v_mov_b32_e32 v25, v32
	v_mov_b32_e32 v26, v32
	v_mov_b32_e32 v27, v32
	v_mov_b32_e32 v20, v32
	v_mov_b32_e32 v21, v32
	v_mov_b32_e32 v22, v32
	v_mov_b32_e32 v23, v32
	v_mov_b32_e32 v17, v32
	v_mov_b32_e32 v18, v32
	v_mov_b32_e32 v19, v32
	v_mov_b32_e32 v9, v32
	s_waitcnt vmcnt(11)
	v_lshlrev_b32_e32 v70, 16, v5
	v_and_b32_e32 v71, 0xffff0000, v5
	v_mov_b32_e32 v5, v3
	s_waitcnt vmcnt(10)
	v_lshlrev_b32_e32 v68, 16, v16
	v_and_b32_e32 v69, 0xffff0000, v16
	s_waitcnt vmcnt(9)
	v_lshlrev_b32_e32 v50, 16, v14
	v_and_b32_e32 v51, 0xffff0000, v14
	s_waitcnt vmcnt(8)
	v_lshlrev_b32_e32 v48, 16, v15
	v_and_b32_e32 v49, 0xffff0000, v15
	s_waitcnt vmcnt(6)
	v_lshlrev_b32_e32 v44, 16, v13
	s_waitcnt vmcnt(5)
	v_lshlrev_b32_e32 v45, 16, v10
	v_lshl_add_u32 v10, v7, 2, s37
	v_lshlrev_b32_e32 v47, 16, v12
	s_waitcnt vmcnt(4)
	v_lshlrev_b32_e32 v46, 16, v8
	v_mov_b32_e32 v8, s37
	v_mad_u32_u24 v11, v7, s2, v8
	s_movk_i32 s2, 0x50
	v_mad_u32_u24 v8, v7, s2, v8
	v_or_b32_e32 v7, 2, v6
	v_or_b32_e32 v6, 3, v6
	v_cmp_gt_u32_e64 s[12:13], v6, v116
	v_or_b32_e32 v6, s30, v116
	v_mul_lo_u32 v6, v6, s2
	v_readlane_b32 s2, v255, 32
	s_add_u32 s20, s2, s25
	v_readlane_b32 s2, v255, 33
	s_addc_u32 s25, s2, 0
	s_add_u32 s20, s20, s31
	s_addc_u32 s25, s25, 0
	s_ashr_i32 s31, s30, 31
	s_lshl_b64 s[30:31], s[30:31], 1
	s_add_u32 s30, s20, s30
	s_addc_u32 s31, s25, s31
	s_add_u32 s20, s42, s23
	s_mul_i32 s25, s21, 0x440
	s_addc_u32 s21, s43, 0
	s_add_u32 s20, s20, s24
	s_movk_i32 s2, 0x110
	s_addc_u32 s21, s21, 0
	v_cmp_gt_u32_e64 s[10:11], v7, v116
	v_lshl_add_u64 v[76:77], s[30:31], 0, v[52:53]
	v_mad_u32_u24 v53, v116, s2, 0
	v_add_u32_e32 v120, 0, v6
	v_lshl_add_u64 v[60:61], s[20:21], 0, v[4:5]
	s_sub_i32 s41, 0, s38
	s_lshl_b32 s42, s22, 1
	v_add_u32_e32 v123, s25, v10
	v_add_u32_e32 v127, s34, v11
	v_add_u32_e32 v122, s34, v8
	s_mov_b32 s43, 0
	v_mov_b32_e32 v16, v32
	v_mov_b32_e32 v12, v32
	v_mov_b32_e32 v13, v32
	v_mov_b32_e32 v14, v32
	v_mov_b32_e32 v15, v32
	v_mov_b32_e32 v8, v32
	v_mov_b32_e32 v10, v32
	v_mov_b32_e32 v11, v32
	v_mov_b32_e32 v4, v32
	v_mov_b32_e32 v5, v32
	v_mov_b32_e32 v6, v32
	v_mov_b32_e32 v7, v32
	s_waitcnt vmcnt(0)
	s_and_b64 s[50:51], s[6:7], exec
	s_cselect_b32 s46, 1, -1
	s_mul_i32 s47, s46, 0x2a00
	s_ashr_i32 s48, s46, 31
	s_mov_b32 s45, 0
	v_readfirstlane_b32 s49, v168
	s_lshr_b32 s49, s49, 6
	s_and_b32 s49, s49, 3
	s_mul_i32 s49, s49, 9728
	s_add_u32 s49, s49, 0x10000
	v_lshl_add_u32 v156, v174, 3, s49
	s_mul_i32 s52, s46, 0xfffd6000
	s_ashr_i32 s53, s52, 31
	s_mul_i32 s80, s46, 0xfffec000
	s_ashr_i32 s81, s80, 31
	s_mul_i32 s54, s46, 0xfffd8a00
	s_ashr_i32 s55, s54, 31
	s_mul_i32 s86, s46, 0xfffed400
	s_ashr_i32 s87, s86, 31
	s_mul_i32 s64, s46, 0xfffdb400
	s_ashr_i32 s65, s64, 31
	s_mul_i32 s92, s46, 0xfffee800
	s_ashr_i32 s93, s92, 31
	s_mul_i32 s66, s46, 0xfffdde00
	s_ashr_i32 s67, s66, 31
	s_mul_i32 s98, s46, 0xfffefc00
	s_ashr_i32 s99, s98, 31
	s_branch .LBB0_162

; __device__ __forceinline__ void scan_hgrn_mfma(const Params& P, unsigned char* LB, int l, int c) {
;     ...
;     for (int tile = 0; tile < NTILES; ++tile) {
;         f32x2 q[4], kk[4], pre[4], suf[4]; float vv[4];
;         { f32x2 fc[4];
; #pragma unroll
;           for (int r = 0; r < 4; ++r) {
;               const float eq0 = 1.f + __expf(fminf(-pq[r].x, 40.f)), ef0 = 1.f + __expf(fminf(-pf[r].x, 40.f)), r0_ = __builtin_amdgcn_rcpf(eq0 * ef0);
;               const float eq1 = 1.f + __expf(fminf(-pq[r].y, 40.f)), ef1 = 1.f + __expf(fminf(-pf[r].y, 40.f)), r1_ = __builtin_amdgcn_rcpf(eq1 * ef1);
;               q[r].x = pq[r].x * (ef0 * r0_) * 0.08838834764831845f; q[r].y = pq[r].y * (ef1 * r1_) * 0.08838834764831845f;
;               const float f0 = lb2.x + (1.f - lb2.x) * (eq0 * r0_), f1 = lb2.y + (1.f - lb2.y) * (eq1 * r1_);
;               kk[r].x = 1.f - f0; kk[r].y = 1.f - f1; fc[r].x = fmaxf(f0, 1e-4f); fc[r].y = fmaxf(f1, 1e-4f); vv[r] = pv[r];
;           }
;           pre[0] = fc[0]; pre[1] = pre[0] * fc[1]; pre[2] = pre[1] * fc[2]; pre[3] = pre[2] * fc[3];
;           suf[3] = (f32x2){1.f, 1.f}; suf[2] = fc[3]; suf[1] = suf[2] * fc[2]; suf[0] = suf[1] * fc[1]; }
;         *(f32x2*)&tot[(cb * 4 + qt) * 128 + k] = pre[3];
.Lhg_unpack:
	s_mov_b32 s45, 1
	s_add_i32 s43, s43, 32
	s_sub_i32 s40, s40, 32
	s_add_i32 s44, s44, 1
	v_lshlrev_b32_e32 v70, 16, v128
	v_and_b32_e32 v71, 0xffff0000, v128
	v_lshlrev_b32_e32 v68, 16, v129
	v_and_b32_e32 v69, 0xffff0000, v129
	v_lshlrev_b32_e32 v50, 16, v131
	v_and_b32_e32 v51, 0xffff0000, v131
	v_lshlrev_b32_e32 v48, 16, v132
	v_and_b32_e32 v49, 0xffff0000, v132
	v_lshlrev_b32_e32 v45, 16, v137
	v_lshlrev_b32_e32 v44, 16, v136
	v_lshlrev_b32_e32 v47, 16, v135
	s_cmpk_eq_i32 s43, 0x8e0
	v_lshlrev_b32_e32 v46, 16, v130
	s_cbranch_scc1 .LBB0_189
.LBB0_162:
	s_cmp_eq_u32 s45, 1
	s_cbranch_scc0 .Lhh_domath
	s_cmp_lg_u64 s[28:29], 0
	s_cbranch_scc1 .Lhh_skipmath
.Lhh_domath:
	v_mul_f32_e32 v37, 0xbfb8aa3b, v66
	v_min_f32_e32 v37, 0x4266d4ca, v37
	v_exp_f32_e32 v38, v37
	v_mul_f32_e32 v36, 0xbfb8aa3b, v70
	v_mul_f32_e32 v37, 0xbfb8aa3b, v71
	v_mul_f32_e32 v39, 0xbfb8aa3b, v67
	v_min_f32_e32 v36, 0x4266d4ca, v36
	v_min_f32_e32 v37, 0x4266d4ca, v37
	v_min_f32_e32 v39, 0x4266d4ca, v39
	v_exp_f32_e32 v36, v36
	v_exp_f32_e32 v39, v39
	v_exp_f32_e32 v37, v37
	v_mul_f32_e32 v41, 0xbfb8aa3b, v65
	v_pk_add_f32 v[94:95], v[38:39], 1.0 op_sel_hi:[1,0]
	v_pk_add_f32 v[36:37], v[36:37], 1.0 op_sel_hi:[1,0]
	v_min_f32_e32 v41, 0x4266d4ca, v41
	v_pk_mul_f32 v[38:39], v[36:37], v[94:95]
	v_exp_f32_e32 v41, v41
	v_rcp_f32_e32 v99, v39
	v_mul_f32_e32 v39, 0xbfb8aa3b, v64
	v_min_f32_e32 v39, 0x4266d4ca, v39
	v_rcp_f32_e32 v98, v38
	v_exp_f32_e32 v40, v39
	v_mul_f32_e32 v38, 0xbfb8aa3b, v68
	v_mul_f32_e32 v39, 0xbfb8aa3b, v69
	v_min_f32_e32 v38, 0x4266d4ca, v38
	v_min_f32_e32 v39, 0x4266d4ca, v39
	v_exp_f32_e32 v38, v38
	v_exp_f32_e32 v39, v39
	v_pk_add_f32 v[86:87], v[40:41], 1.0 op_sel_hi:[1,0]
	v_pk_mul_f32 v[36:37], v[36:37], v[98:99]
	v_pk_add_f32 v[38:39], v[38:39], 1.0 op_sel_hi:[1,0]
	v_pk_fma_f32 v[102:103], v[54:55], v[36:37], v[0:1]
	v_pk_mul_f32 v[40:41], v[38:39], v[86:87]
	v_rcp_f32_e32 v88, v40
	v_rcp_f32_e32 v89, v41
	v_mul_f32_e32 v41, 0xbfb8aa3b, v63
	v_min_f32_e32 v41, 0x4266d4ca, v41
	v_pk_mul_f32 v[36:37], v[38:39], v[88:89]
	v_mul_f32_e32 v39, 0xbfb8aa3b, v62
	v_min_f32_e32 v39, 0x4266d4ca, v39
	v_exp_f32_e32 v40, v39
	v_mul_f32_e32 v38, 0xbfb8aa3b, v50
	v_mul_f32_e32 v39, 0xbfb8aa3b, v51
	v_min_f32_e32 v38, 0x4266d4ca, v38
	v_min_f32_e32 v39, 0x4266d4ca, v39
	v_exp_f32_e32 v38, v38
	v_exp_f32_e32 v41, v41
	v_exp_f32_e32 v39, v39
	v_pk_fma_f32 v[92:93], v[54:55], v[36:37], v[0:1]
	v_pk_add_f32 v[80:81], v[40:41], 1.0 op_sel_hi:[1,0]
	v_pk_add_f32 v[36:37], v[38:39], 1.0 op_sel_hi:[1,0]
	v_pk_mul_f32 v[38:39], v[36:37], v[80:81]
	v_mul_f32_e32 v41, 0xbfb8aa3b, v59
	v_rcp_f32_e32 v85, v39
	v_mul_f32_e32 v39, 0xbfb8aa3b, v58
	v_min_f32_e32 v39, 0x4266d4ca, v39
	v_rcp_f32_e32 v84, v38
	v_exp_f32_e32 v40, v39
	v_mul_f32_e32 v38, 0xbfb8aa3b, v48
	v_mul_f32_e32 v39, 0xbfb8aa3b, v49
	v_min_f32_e32 v38, 0x4266d4ca, v38
	v_min_f32_e32 v39, 0x4266d4ca, v39
	v_min_f32_e32 v41, 0x4266d4ca, v41
	v_exp_f32_e32 v38, v38
	v_exp_f32_e32 v41, v41
	v_exp_f32_e32 v39, v39
	v_pk_add_f32 v[72:73], v[40:41], 1.0 op_sel_hi:[1,0]
	v_pk_add_f32 v[38:39], v[38:39], 1.0 op_sel_hi:[1,0]
	v_pk_mul_f32 v[40:41], v[38:39], v[72:73]
	v_rcp_f32_e32 v74, v40
	v_rcp_f32_e32 v75, v41
	s_nop 0
	v_pk_mul_f32 v[38:39], v[38:39], v[74:75]
	v_pk_fma_f32 v[78:79], v[54:55], v[38:39], v[0:1]
	v_pk_mul_f32 v[36:37], v[36:37], v[84:85]
	v_max_f32_e32 v106, 0x38d1b717, v102
	v_max_f32_e32 v107, 0x38d1b717, v103
	v_max_f32_e32 v110, 0x38d1b717, v92
	v_max_f32_e32 v111, 0x38d1b717, v93
	v_pk_fma_f32 v[90:91], v[54:55], v[36:37], v[0:1]
	v_max_f32_e32 v36, 0x38d1b717, v90
	v_max_f32_e32 v37, 0x38d1b717, v91
	v_pk_mul_f32 v[108:109], v[110:111], v[106:107]
	v_max_f32_e32 v100, 0x38d1b717, v78
	v_max_f32_e32 v101, 0x38d1b717, v79
	v_pk_mul_f32 v[96:97], v[36:37], v[108:109]
	v_pk_mul_f32 v[82:83], v[100:101], v[96:97]
	ds_write_b64 v125, v[82:83] offset:58368
	s_cmp_eq_u32 s45, 1
	s_cbranch_scc0 .Lhh_skipmath
	v_lshlrev_b32_e32 v144, 16, v239
	v_and_b32_e32 v145, 0xffff0000, v239
	v_lshlrev_b32_e32 v146, 16, v238
	v_and_b32_e32 v147, 0xffff0000, v238
	v_lshlrev_b32_e32 v148, 16, v237
	v_and_b32_e32 v149, 0xffff0000, v237
	v_lshlrev_b32_e32 v150, 16, v236
	v_and_b32_e32 v151, 0xffff0000, v236
	v_mul_f32_e32 v195, 0xbfb8aa3b, v240
	v_min_f32_e32 v195, 0x4266d4ca, v195
	v_exp_f32_e32 v196, v195
	v_mul_f32_e32 v194, 0xbfb8aa3b, v150
	v_mul_f32_e32 v195, 0xbfb8aa3b, v151
	v_mul_f32_e32 v197, 0xbfb8aa3b, v241
	v_min_f32_e32 v194, 0x4266d4ca, v194
	v_min_f32_e32 v195, 0x4266d4ca, v195
	v_min_f32_e32 v197, 0x4266d4ca, v197
	v_exp_f32_e32 v194, v194
	v_exp_f32_e32 v197, v197
	v_exp_f32_e32 v195, v195
	v_mul_f32_e32 v199, 0xbfb8aa3b, v243
	v_pk_add_f32 v[220:221], v[196:197], 1.0 op_sel_hi:[1,0]
	v_pk_add_f32 v[194:195], v[194:195], 1.0 op_sel_hi:[1,0]
	v_min_f32_e32 v199, 0x4266d4ca, v199
	v_pk_mul_f32 v[196:197], v[194:195], v[220:221]
	v_exp_f32_e32 v199, v199
	v_rcp_f32_e32 v225, v197
	v_mul_f32_e32 v197, 0xbfb8aa3b, v242
	v_min_f32_e32 v197, 0x4266d4ca, v197
	v_rcp_f32_e32 v224, v196
	v_exp_f32_e32 v198, v197
	v_mul_f32_e32 v196, 0xbfb8aa3b, v148
	v_mul_f32_e32 v197, 0xbfb8aa3b, v149
	v_min_f32_e32 v196, 0x4266d4ca, v196
	v_min_f32_e32 v197, 0x4266d4ca, v197
	v_exp_f32_e32 v196, v196
	v_exp_f32_e32 v197, v197
	v_pk_add_f32 v[212:213], v[198:199], 1.0 op_sel_hi:[1,0]
	v_pk_mul_f32 v[194:195], v[194:195], v[224:225]
	v_pk_add_f32 v[196:197], v[196:197], 1.0 op_sel_hi:[1,0]
	v_pk_fma_f32 v[228:229], v[54:55], v[194:195], v[0:1]
	v_pk_mul_f32 v[198:199], v[196:197], v[212:213]
	v_rcp_f32_e32 v214, v198
	v_rcp_f32_e32 v215, v199
	v_mul_f32_e32 v199, 0xbfb8aa3b, v141
; __device__ __forceinline__ void scan_hgrn_mfma(const Params& P, unsigned char* LB, int l, int c) {
;     ...
;         { f32x2 fc[4];
; #pragma unroll
;           for (int r = 0; r < 4; ++r) {
;               const float eq0 = 1.f + __expf(fminf(-pq[r].x, 40.f)), ef0 = 1.f + __expf(fminf(-pf[r].x, 40.f)), r0_ = __builtin_amdgcn_rcpf(eq0 * ef0);
;               const float eq1 = 1.f + __expf(fminf(-pq[r].y, 40.f)), ef1 = 1.f + __expf(fminf(-pf[r].y, 40.f)), r1_ = __builtin_amdgcn_rcpf(eq1 * ef1);
;               q[r].x = pq[r].x * (ef0 * r0_) * 0.08838834764831845f; q[r].y = pq[r].y * (ef1 * r1_) * 0.08838834764831845f;
;               const float f0 = lb2.x + (1.f - lb2.x) * (eq0 * r0_), f1 = lb2.y + (1.f - lb2.y) * (eq1 * r1_);
;               kk[r].x = 1.f - f0; kk[r].y = 1.f - f1; fc[r].x = fmaxf(f0, 1e-4f); fc[r].y = fmaxf(f1, 1e-4f); vv[r] = pv[r];
;           }
;           pre[0] = fc[0]; pre[1] = pre[0] * fc[1]; pre[2] = pre[1] * fc[2]; pre[3] = pre[2] * fc[3];
;           suf[3] = (f32x2){1.f, 1.f}; suf[2] = fc[3]; suf[1] = suf[2] * fc[2]; suf[0] = suf[1] * fc[1]; }
;         *(f32x2*)&tot[(cb * 4 + qt) * 128 + k] = pre[3];
	v_min_f32_e32 v199, 0x4266d4ca, v199
	v_pk_mul_f32 v[194:195], v[196:197], v[214:215]
	v_mul_f32_e32 v197, 0xbfb8aa3b, v140
	v_min_f32_e32 v197, 0x4266d4ca, v197
	v_exp_f32_e32 v198, v197
	v_mul_f32_e32 v196, 0xbfb8aa3b, v146
	v_mul_f32_e32 v197, 0xbfb8aa3b, v147
	v_min_f32_e32 v196, 0x4266d4ca, v196
	v_min_f32_e32 v197, 0x4266d4ca, v197
	v_exp_f32_e32 v196, v196
	v_exp_f32_e32 v199, v199
	v_exp_f32_e32 v197, v197
	v_pk_fma_f32 v[218:219], v[54:55], v[194:195], v[0:1]
	v_pk_add_f32 v[206:207], v[198:199], 1.0 op_sel_hi:[1,0]
	v_pk_add_f32 v[194:195], v[196:197], 1.0 op_sel_hi:[1,0]
	v_pk_mul_f32 v[196:197], v[194:195], v[206:207]
	v_mul_f32_e32 v199, 0xbfb8aa3b, v143
	v_rcp_f32_e32 v211, v197
	v_mul_f32_e32 v197, 0xbfb8aa3b, v142
	v_min_f32_e32 v197, 0x4266d4ca, v197
	v_rcp_f32_e32 v210, v196
	v_exp_f32_e32 v198, v197
	v_mul_f32_e32 v196, 0xbfb8aa3b, v144
	v_mul_f32_e32 v197, 0xbfb8aa3b, v145
	v_min_f32_e32 v196, 0x4266d4ca, v196
	v_min_f32_e32 v197, 0x4266d4ca, v197
	v_min_f32_e32 v199, 0x4266d4ca, v199
	v_exp_f32_e32 v196, v196
	v_exp_f32_e32 v199, v199
	v_exp_f32_e32 v197, v197
	v_pk_add_f32 v[200:201], v[198:199], 1.0 op_sel_hi:[1,0]
	v_pk_add_f32 v[196:197], v[196:197], 1.0 op_sel_hi:[1,0]
	v_pk_mul_f32 v[198:199], v[196:197], v[200:201]
	v_rcp_f32_e32 v202, v198
	v_rcp_f32_e32 v203, v199
	s_nop 0
	v_pk_mul_f32 v[196:197], v[196:197], v[202:203]
	v_pk_fma_f32 v[204:205], v[54:55], v[196:197], v[0:1]
	v_pk_mul_f32 v[194:195], v[194:195], v[210:211]
	v_max_f32_e32 v230, 0x38d1b717, v228
	v_max_f32_e32 v231, 0x38d1b717, v229
	v_max_f32_e32 v234, 0x38d1b717, v218
	v_max_f32_e32 v235, 0x38d1b717, v219
	v_pk_fma_f32 v[216:217], v[54:55], v[194:195], v[0:1]
	v_max_f32_e32 v194, 0x38d1b717, v216
	v_max_f32_e32 v195, 0x38d1b717, v217
	v_pk_mul_f32 v[232:233], v[234:235], v[230:231]
	v_max_f32_e32 v226, 0x38d1b717, v204
	v_max_f32_e32 v227, 0x38d1b717, v205
	v_pk_mul_f32 v[222:223], v[194:195], v[232:233]
	v_pk_mul_f32 v[208:209], v[226:227], v[222:223]
	ds_write_b64 v125, v[208:209] offset:56320
	ds_write_b64 v156, v[194:195] offset:0
	ds_write_b64 v156, v[200:201] offset:512
	ds_write_b64 v156, v[202:203] offset:1024
	ds_write_b64 v156, v[204:205] offset:1536
	ds_write_b64 v156, v[206:207] offset:2048
	ds_write_b64 v156, v[208:209] offset:2560
	ds_write_b64 v156, v[210:211] offset:3072
	ds_write_b64 v156, v[212:213] offset:3584
	ds_write_b64 v156, v[214:215] offset:4096
	ds_write_b64 v156, v[216:217] offset:4608
	ds_write_b64 v156, v[218:219] offset:5120
	ds_write_b64 v156, v[220:221] offset:5632
	ds_write_b64 v156, v[222:223] offset:6144
	ds_write_b64 v156, v[224:225] offset:6656
	ds_write_b64 v156, v[226:227] offset:7168
	ds_write_b64 v156, v[228:229] offset:7680
	ds_write_b64 v156, v[230:231] offset:8192
	ds_write_b64 v156, v[232:233] offset:8704
	ds_write_b64 v156, v[234:235] offset:9216
; __device__ __forceinline__ void scan_hgrn_mfma(const Params& P, unsigned char* LB, int l, int c) {
;     ...
;         __syncthreads();
;         if (tile + 1 < NTILES) HGM_LOAD(tile + 1);
;         {
;             const f32x2 t0 = *(const f32x2*)&tot[(cb * 4 + 0) * 128 + k], t1 = *(const f32x2*)&tot[(cb * 4 + 1) * 128 + k], t2 = *(const f32x2*)&tot[(cb * 4 + 2) * 128 + k], t3 = *(const f32x2*)&tot[(cb * 4 + 3) * 128 + k];
;             const f32x2 Pm = t0 * t1, T23 = t2 * t3;
;             unsigned char* C = OP + cb * CL::SIZE;
;             float kw0[4], kw1[4];
; #pragma unroll
;             for (int r = 0; r < 4; ++r) {
;                 const int t = qt * 4 + r;
;                 f32x2 R, iR;
;                 if (qt >= 2) { R = pre[r]; if (qt == 3) R *= t2; iR.x = __builtin_amdgcn_rcpf(R.x); iR.y = __builtin_amdgcn_rcpf(R.y); }
;                 else { iR = suf[r]; if (qt == 0) iR *= t1; R.x = __builtin_amdgcn_rcpf(iR.x); R.y = __builtin_amdgcn_rcpf(iR.y); }
.Lhh_skipmath:
	s_add_i32 s22, s38, s43
	s_add_i32 s20, s22, 32
	s_add_i32 s21, s22, 0xffffff20
	s_cmpk_lt_i32 s20, 0x100
	s_cselect_b32 s23, 0xff, s33
	s_cselect_b32 s24, s20, s21
	s_cselect_b32 s25, s39, s36
	s_add_i32 s20, s41, s23
	s_add_i32 s20, s20, s40
	s_sub_i32 s23, s20, 32
	s_and_b64 s[20:21], s[6:7], exec
	s_cselect_b32 s20, s24, s23
	s_add_i32 s23, s20, s25
	s_mul_i32 s21, s23, 0x2a00
	s_mul_hi_i32 s20, s23, 0x2a00
	s_add_u32 s21, s94, s21
	s_addc_u32 s24, s95, s20
	s_add_u32 s20, s21, s42
	s_addc_u32 s21, s24, 0
	s_mov_b64 s[50:51], s[20:21]
	v_lshl_add_u64 v[38:39], s[20:21], 0, v[2:3]
	v_mad_i64_i32 v[40:41], s[20:21], s23, v191, v[60:61]
	s_add_u32 s50, s50, s47
	s_addc_u32 s51, s51, s48
	s_add_i32 s24, s23, s46
	v_lshl_add_u64 v[42:43], s[50:51], 0, v[2:3]
	v_mad_i64_i32 v[58:59], s[20:21], s24, v191, v[60:61]
	s_mov_b32 s2, 0x26201000
	v_add_co_u32_e32 v38, vcc, s2, v38
	s_nop 1
	v_addc_co_u32_e32 v39, vcc, 0, v39, vcc
	v_add_co_u32_e32 v42, vcc, s2, v42
	s_add_u32 s50, s50, s47
	s_addc_u32 s51, s51, s48
	s_add_i32 s25, s24, s46
	s_mov_b64 s[20:21], s[50:51]
	s_waitcnt lgkmcnt(0)
	s_barrier
	s_cmp_eq_u32 s45, 1
	s_cbranch_scc0 .Lhh_noread
	s_cmp_lg_u64 s[28:29], 0
	s_cbranch_scc0 .Lhh_noread
	ds_read_b64 v[36:37], v156 offset:0
	ds_read_b64 v[72:73], v156 offset:512
	ds_read_b64 v[74:75], v156 offset:1024
	ds_read_b64 v[78:79], v156 offset:1536
	ds_read_b64 v[80:81], v156 offset:2048
	ds_read_b64 v[82:83], v156 offset:2560
	ds_read_b64 v[84:85], v156 offset:3072
	ds_read_b64 v[86:87], v156 offset:3584
	ds_read_b64 v[88:89], v156 offset:4096
	ds_read_b64 v[90:91], v156 offset:4608
	ds_read_b64 v[92:93], v156 offset:5120
	ds_read_b64 v[94:95], v156 offset:5632
	ds_read_b64 v[96:97], v156 offset:6144
	ds_read_b64 v[98:99], v156 offset:6656
	ds_read_b64 v[100:101], v156 offset:7168
	ds_read_b64 v[102:103], v156 offset:7680
	ds_read_b64 v[106:107], v156 offset:8192
	ds_read_b64 v[108:109], v156 offset:8704
	ds_read_b64 v[110:111], v156 offset:9216
	s_waitcnt lgkmcnt(0)
.Lhh_noread:
	s_cmp_lg_u64 s[28:29], 0
	s_cbranch_scc1 .Lhh_noload
	v_lshl_add_u64 v[152:153], v[38:39], 0, s[52:53]
	v_lshl_add_u64 v[154:155], v[40:41], 0, s[80:81]
	global_load_dword v236, v[152:153], off offset:2048
	global_load_dwordx2 v[240:241], v[154:155], off offset:64
	v_lshl_add_u64 v[152:153], v[38:39], 0, s[54:55]
	v_lshl_add_u64 v[154:155], v[40:41], 0, s[86:87]
	global_load_dword v237, v[152:153], off offset:2048
	global_load_dwordx2 v[242:243], v[154:155], off offset:64
	v_lshl_add_u64 v[152:153], v[38:39], 0, s[64:65]
	v_lshl_add_u64 v[154:155], v[40:41], 0, s[92:93]
	global_load_dword v238, v[152:153], off offset:2048
	global_load_dwordx2 v[140:141], v[154:155], off offset:64
	v_lshl_add_u64 v[152:153], v[38:39], 0, s[66:67]
	v_lshl_add_u64 v[154:155], v[40:41], 0, s[98:99]
	global_load_dword v239, v[152:153], off offset:2048
	global_load_dwordx2 v[142:143], v[154:155], off offset:64
.Lhh_noload:
	v_addc_co_u32_e32 v43, vcc, 0, v43, vcc
	global_load_dword v128, v[38:39], off offset:2048
	global_load_dwordx2 v[66:67], v[40:41], off offset:64
	global_load_dword v129, v[42:43], off offset:2048
	global_load_dwordx2 v[64:65], v[58:59], off offset:64
	v_lshl_add_u64 v[38:39], s[20:21], 0, v[2:3]
	v_mad_i64_i32 v[40:41], s[20:21], s25, v191, v[60:61]
	v_add_co_u32_e32 v38, vcc, s2, v38
	s_nop 1
	v_addc_co_u32_e32 v39, vcc, 0, v39, vcc
	s_add_u32 s50, s50, s47
	s_addc_u32 s51, s51, s48
	s_add_i32 s22, s25, s46
	v_lshl_add_u64 v[42:43], s[50:51], 0, v[2:3]
	v_add_co_u32_e32 v42, vcc, s2, v42
	v_mad_i64_i32 v[58:59], s[20:21], s22, v191, v[60:61]
	s_nop 0
	v_addc_co_u32_e32 v43, vcc, 0, v43, vcc
	global_load_dword v131, v[38:39], off offset:2048
	global_load_dwordx2 v[62:63], v[40:41], off offset:64
	global_load_dword v132, v[42:43], off offset:2048
	s_nop 0
	global_load_dwordx2 v[58:59], v[58:59], off offset:64
	v_mad_i64_i32 v[38:39], s[20:21], s23, v190, v[56:57]
	v_mad_i64_i32 v[40:41], s[20:21], s24, v190, v[56:57]
	v_mad_i64_i32 v[42:43], s[20:21], s25, v190, v[56:57]
	v_mad_i64_i32 v[104:105], s[20:21], s22, v190, v[56:57]
	global_load_ushort v136, v[38:39], off
	global_load_ushort v137, v[40:41], off
	global_load_ushort v130, v[42:43], off
	global_load_ushort v135, v[104:105], off
	v_pk_mul_f32 v[112:113], v[100:101], v[36:37]
	ds_read2st64_b64 v[40:43], v124 offset0:114 offset1:115
	ds_read2st64_b64 v[36:39], v124 offset0:116 offset1:117
	s_mov_b64 s[20:21], -1
	s_and_b64 vcc, exec, s[26:27]
	s_cbranch_vccz .LBB0_164
	v_pk_mul_f32 v[104:105], v[110:111], v[112:113]
	s_mov_b64 s[20:21], 0
	s_waitcnt lgkmcnt(1)
	v_pk_mul_f32 v[110:111], v[104:105], v[42:43]
	s_nop 0
	v_cndmask_b32_e64 v105, v105, v111, s[18:19]
	v_cndmask_b32_e64 v104, v104, v110, s[18:19]
	v_rcp_f32_e32 v114, v104
	v_rcp_f32_e32 v115, v105
